# also the layer-0 f32-residual path: ssq shuffles via permlane swaps (with store-data WAR pad)
# baseline (speedup 1.0000x reference)
; __device__ __forceinline__ unsigned cvt_pk_bf16(float lo, float hi) { unsigned r; asm volatile("v_cvt_pk_bf16_f32 %0, %1, %2" : "=v"(r) : "v"(lo), "v"(hi)); return r; }
;     __device__ __forceinline__ void finish_half(const f32x4 (&acc)[2][2][4][2], const f32x4 (&r)[4][2][2], const Unit& u, int ai, int rl0, int col0, int wc, int fq) const {
;     ...
;         for (int m = 0; m < 4; ++m) { const size_t row = (size_t)(u.pm * BM + rl0 + ai * HALF + m * 16); const size_t off = row * 1024 + col0; float q = 0.f;
; #pragma unroll
;             for (int bj = 0; bj < 2; ++bj) {
;                 const f32x4 v0 = acc[ai][bj][m][0] + r[m][bj][0], v1 = acc[ai][bj][m][1] + r[m][bj][1];
;                 if (out32) { *(f32x4*)(out32 + off + bj * HALF) = v0; *(f32x4*)(out32 + off + bj * HALF + 4) = v1; }
;                 q += (v0[0] * v0[0] + v0[1] * v0[1]) + (v0[2] * v0[2] + v0[3] * v0[3]) + (v1[0] * v1[0] + v1[1] * v1[1]) + (v1[2] * v1[2] + v1[3] * v1[3]);
;                 u32x4 w; w.x = cvt_pk_bf16(v0[0], v0[1]); w.y = cvt_pk_bf16(v0[2], v0[3]); w.z = cvt_pk_bf16(v1[0], v1[1]); w.w = cvt_pk_bf16(v1[2], v1[3]);
;                 *(u32x4*)(hb + off + bj * HALF) = w; }
;             q += __shfl_xor(q, 16); q += __shfl_xor(q, 32);
;             if (fq == 0) ssq[row * 16 + u.pn * 4 + wc] = q; }
;     __device__ __forceinline__ void operator()(const f32x4 (&acc)[2][2][4][2], const Unit& u, int wr, int wc, int fr, int fq) const {
;     ...
;         if (res32) {
; #pragma unroll
;             for (int ai = 0; ai < 2; ++ai) { f32x4 r[4][2][2];
; #pragma unroll
;                 for (int m = 0; m < 4; ++m)
; #pragma unroll
;                     for (int bj = 0; bj < 2; ++bj) { const size_t off = (size_t)(u.pm * BM + rl0 + ai * HALF + m * 16) * 1024 + col0 + bj * HALF;
;                         r[m][bj][0] = *(const f32x4*)(res32 + off); r[m][bj][1] = *(const f32x4*)(res32 + off + 4); }
;                 finish_half(acc, r, u, ai, rl0, col0, wc, fq); }
.LBB0_362:
	s_lshl_b32 s51, s80, 8
	v_mov_b32_e32 v130, v195
	v_mov_b32_e32 v217, v193
	s_or_b32 s51, s51, s37
	s_andn2_b64 vcc, exec, s[46:47]
	v_add_u32_e32 v216, s36, v130
	v_lshl_add_u32 v206, v217, 3, s51
	s_lshl_b32 s51, s70, 8
	v_add_u32_e32 v208, s51, v216
	v_ashrrev_i32_e32 v207, 31, v206
	v_cmp_eq_u32_e64 s[58:59], 0, v217
	v_ashrrev_i32_e32 v209, 31, v208
	s_cbranch_vccnz .LBB0_380
	v_lshl_add_u64 v[178:179], v[206:207], 2, s[28:29]
	v_lshlrev_b64 v[130:131], 12, v[208:209]
	v_lshl_add_u64 v[138:139], v[178:179], 0, v[130:131]
	global_load_dwordx4 v[180:183], v[138:139], off
	global_load_dwordx4 v[210:213], v[138:139], off offset:16
	global_load_dwordx4 v[218:221], v[138:139], off offset:512
	global_load_dwordx4 v[222:225], v[138:139], off offset:528
	s_mov_b64 s[60:61], 0x10000
	v_lshl_add_u64 v[140:141], v[138:139], 0, s[60:61]
	v_add_co_u32_e32 v142, vcc, 0x10000, v138
	s_mov_b64 s[60:61], 0x20000
	v_lshl_add_u64 v[144:145], v[138:139], 0, s[60:61]
	s_mov_b64 s[60:61], 0x30000
	v_addc_co_u32_e32 v143, vcc, 0, v139, vcc
	s_mov_b32 s53, 0x20000
	v_lshl_add_u64 v[184:185], v[138:139], 0, s[60:61]
	global_load_dwordx4 v[170:173], v[140:141], off offset:16
	global_load_dwordx4 v[162:165], v[140:141], off offset:512
	v_add_co_u32_e32 v154, vcc, s53, v138
	global_load_dwordx4 v[150:153], v[144:145], off offset:16
	global_load_dwordx4 v[146:149], v[144:145], off offset:512
	global_load_dwordx4 v[134:137], v[184:185], off offset:16
	global_load_dwordx4 v[130:133], v[184:185], off offset:512
	global_load_dwordx4 v[174:177], v[142:143], off
	global_load_dwordx4 v[166:169], v[140:141], off offset:528
	v_addc_co_u32_e32 v155, vcc, 0, v139, vcc
	s_mov_b32 s53, 0x30000
	v_add_co_u32_e32 v138, vcc, s53, v138
	global_load_dwordx4 v[158:161], v[154:155], off
	s_nop 0
	global_load_dwordx4 v[154:157], v[144:145], off offset:528
	v_addc_co_u32_e32 v139, vcc, 0, v139, vcc
	global_load_dwordx4 v[142:145], v[138:139], off
	s_nop 0
	global_load_dwordx4 v[138:141], v[184:185], off offset:528
	v_lshlrev_b64 v[184:185], 11, v[208:209]
	v_lshl_add_u64 v[184:185], s[40:41], 0, v[184:185]
	s_lshl_b32 s60, s80, 2
	s_ashr_i32 s61, s60, 31
	s_waitcnt vmcnt(0)
	v_pk_add_f32 v[226:227], v[128:129], v[182:183]
	v_pk_add_f32 v[228:229], v[126:127], v[180:181]
	v_pk_add_f32 v[212:213], v[124:125], v[212:213]
	v_pk_add_f32 v[210:211], v[122:123], v[210:211]
	v_pk_add_f32 v[220:221], v[120:121], v[220:221]
	v_pk_add_f32 v[218:219], v[118:119], v[218:219]
	v_pk_add_f32 v[222:223], v[114:115], v[222:223]
	v_mul_f32_e32 v236, v229, v229
	v_mul_f32_e32 v237, v227, v227
	v_mul_f32_e32 v238, v211, v211
	v_mul_f32_e32 v239, v213, v213
	v_cvt_pk_bf16_f32 v180, v228, v229
	v_cvt_pk_bf16_f32 v181, v226, v227
	v_cvt_pk_bf16_f32 v182, v210, v211
	v_cvt_pk_bf16_f32 v183, v212, v213
	v_mul_f32_e32 v211, v219, v219
	v_mul_f32_e32 v213, v221, v221
	v_pk_add_f32 v[224:225], v[116:117], v[224:225]
	v_mul_f32_e32 v227, v223, v223
	v_fmac_f32_e32 v236, v228, v228
	v_fmac_f32_e32 v237, v226, v226
	v_fmac_f32_e32 v211, v218, v218
	v_fmac_f32_e32 v213, v220, v220
	v_mul_f32_e32 v229, v225, v225
	v_fmac_f32_e32 v238, v210, v210
	v_fmac_f32_e32 v227, v222, v222
	v_add_f32_e32 v210, v236, v237
	v_add_f32_e32 v211, v211, v213
	v_fmac_f32_e32 v239, v212, v212
	v_fmac_f32_e32 v229, v224, v224
	v_add_f32_e32 v210, v210, v238
	v_add_f32_e32 v211, v211, v227
	v_add_f32_e32 v210, v239, v210
	v_add_f32_e32 v211, v229, v211
	v_add_f32_e32 v212, v210, v211
	v_mov_b32_e32 v213, v212
	v_mov_b32_e32 v247, v212
	s_nop 1
	v_permlane16_swap_b32_e32 v247, v213
	v_lshl_add_u64 v[210:211], v[206:207], 1, v[184:185]
	global_store_dwordx4 v[210:211], v[180:183], off
	s_waitcnt lgkmcnt(0)
	s_nop 0
	v_add_f32_e32 v180, v212, v213
	v_mov_b32_e32 v181, v180
	v_mov_b32_e32 v247, v180
	s_nop 1
	v_permlane32_swap_b32_e32 v247, v181
	v_cvt_pk_bf16_f32 v182, v218, v219
	v_cvt_pk_bf16_f32 v183, v220, v221
	v_cvt_pk_bf16_f32 v184, v222, v223
	v_cvt_pk_bf16_f32 v185, v224, v225
	global_store_dwordx4 v[210:211], v[182:185], off offset:256
	s_and_saveexec_b64 s[62:63], s[58:59]
	s_cbranch_execz .LBB0_365
	v_lshlrev_b64 v[182:183], 6, v[208:209]
	v_lshl_add_u64 v[182:183], s[42:43], 0, v[182:183]
	v_lshl_add_u64 v[182:183], s[60:61], 2, v[182:183]
	s_lshl_b32 s70, s87, 2
	v_lshl_add_u64 v[182:183], v[182:183], 0, s[70:71]
	s_waitcnt lgkmcnt(0)
	v_add_f32_e32 v180, v180, v181
	global_store_dword v[182:183], v180, off
; __device__ __forceinline__ unsigned cvt_pk_bf16(float lo, float hi) { unsigned r; asm volatile("v_cvt_pk_bf16_f32 %0, %1, %2" : "=v"(r) : "v"(lo), "v"(hi)); return r; }
;     __device__ __forceinline__ void finish_half(const f32x4 (&acc)[2][2][4][2], const f32x4 (&r)[4][2][2], const Unit& u, int ai, int rl0, int col0, int wc, int fq) const {
;     ...
;         for (int m = 0; m < 4; ++m) { const size_t row = (size_t)(u.pm * BM + rl0 + ai * HALF + m * 16); const size_t off = row * 1024 + col0; float q = 0.f;
; #pragma unroll
;             for (int bj = 0; bj < 2; ++bj) {
;                 const f32x4 v0 = acc[ai][bj][m][0] + r[m][bj][0], v1 = acc[ai][bj][m][1] + r[m][bj][1];
;                 if (out32) { *(f32x4*)(out32 + off + bj * HALF) = v0; *(f32x4*)(out32 + off + bj * HALF + 4) = v1; }
;                 q += (v0[0] * v0[0] + v0[1] * v0[1]) + (v0[2] * v0[2] + v0[3] * v0[3]) + (v1[0] * v1[0] + v1[1] * v1[1]) + (v1[2] * v1[2] + v1[3] * v1[3]);
;                 u32x4 w; w.x = cvt_pk_bf16(v0[0], v0[1]); w.y = cvt_pk_bf16(v0[2], v0[3]); w.z = cvt_pk_bf16(v1[0], v1[1]); w.w = cvt_pk_bf16(v1[2], v1[3]);
;                 *(u32x4*)(hb + off + bj * HALF) = w; }
;             q += __shfl_xor(q, 16); q += __shfl_xor(q, 32);
;             if (fq == 0) ssq[row * 16 + u.pn * 4 + wc] = q; }
.LBB0_365:
	s_or_b64 exec, exec, s[62:63]
	v_pk_add_f32 v[176:177], v[112:113], v[176:177]
	v_pk_add_f32 v[174:175], v[110:111], v[174:175]
	v_pk_add_f32 v[182:183], v[108:109], v[172:173]
	v_pk_add_f32 v[172:173], v[106:107], v[170:171]
	v_mul_f32_e32 v170, v175, v175
	v_mul_f32_e32 v171, v177, v177
	v_fmac_f32_e32 v170, v174, v174
	v_fmac_f32_e32 v171, v176, v176
	v_add_f32_e32 v170, v170, v171
	v_mul_f32_e32 v171, v173, v173
	v_fmac_f32_e32 v171, v172, v172
	v_add_f32_e32 v170, v170, v171
	v_mul_f32_e32 v171, v183, v183
	v_fmac_f32_e32 v171, v182, v182
	v_add_f32_e32 v184, v171, v170
	v_cvt_pk_bf16_f32 v170, v174, v175
	v_cvt_pk_bf16_f32 v171, v176, v177
	v_pk_add_f32 v[176:177], v[104:105], v[164:165]
	v_pk_add_f32 v[162:163], v[102:103], v[162:163]
	v_mul_f32_e32 v165, v177, v177
	v_mul_f32_e32 v164, v163, v163
	v_pk_add_f32 v[166:167], v[98:99], v[166:167]
	v_fmac_f32_e32 v164, v162, v162
	v_fmac_f32_e32 v165, v176, v176
	v_add_f32_e32 v164, v164, v165
	v_mul_f32_e32 v165, v167, v167
	v_pk_add_f32 v[168:169], v[100:101], v[168:169]
	v_fmac_f32_e32 v165, v166, v166
	v_add_f32_e32 v164, v164, v165
	v_mul_f32_e32 v165, v169, v169
	v_fmac_f32_e32 v165, v168, v168
	v_add_f32_e32 v164, v165, v164
	s_or_b32 s53, s51, 16
	v_cvt_pk_bf16_f32 v172, v172, v173
	v_cvt_pk_bf16_f32 v173, v182, v183
	v_add_f32_e32 v182, v184, v164
	v_add_u32_e32 v180, s53, v216
	v_mov_b32_e32 v183, v182
	v_mov_b32_e32 v247, v182
	s_nop 1
	v_permlane16_swap_b32_e32 v247, v183
	s_waitcnt lgkmcnt(1)
	v_ashrrev_i32_e32 v181, 31, v180
	v_lshlrev_b64 v[174:175], 11, v[180:181]
	v_lshl_add_u64 v[164:165], s[40:41], 0, v[174:175]
	v_lshl_add_u64 v[174:175], v[206:207], 1, v[164:165]
	global_store_dwordx4 v[174:175], v[170:173], off
	v_cvt_pk_bf16_f32 v164, v162, v163
	s_waitcnt lgkmcnt(0)
	v_add_f32_e32 v162, v182, v183
	v_mov_b32_e32 v163, v162
	v_mov_b32_e32 v247, v162
	s_nop 1
	v_permlane32_swap_b32_e32 v247, v163
	v_cvt_pk_bf16_f32 v165, v176, v177
	v_cvt_pk_bf16_f32 v166, v166, v167
	v_cvt_pk_bf16_f32 v167, v168, v169
	global_store_dwordx4 v[174:175], v[164:167], off offset:256
	s_and_saveexec_b64 s[62:63], s[58:59]
	s_cbranch_execz .LBB0_367
	v_lshlrev_b64 v[164:165], 6, v[180:181]
	v_lshl_add_u64 v[164:165], s[42:43], 0, v[164:165]
	v_lshl_add_u64 v[164:165], s[60:61], 2, v[164:165]
	s_lshl_b32 s70, s87, 2
	v_lshl_add_u64 v[164:165], v[164:165], 0, s[70:71]
	s_waitcnt lgkmcnt(0)
	v_add_f32_e32 v162, v162, v163
	global_store_dword v[164:165], v162, off
.LBB0_367:
	s_or_b64 exec, exec, s[62:63]
	v_pk_add_f32 v[160:161], v[96:97], v[160:161]
	v_pk_add_f32 v[158:159], v[94:95], v[158:159]
	v_pk_add_f32 v[164:165], v[92:93], v[152:153]
	v_pk_add_f32 v[152:153], v[90:91], v[150:151]
	v_mul_f32_e32 v150, v159, v159
	v_mul_f32_e32 v151, v161, v161
	v_fmac_f32_e32 v150, v158, v158
	v_fmac_f32_e32 v151, v160, v160
	v_add_f32_e32 v150, v150, v151
	v_mul_f32_e32 v151, v153, v153
	v_fmac_f32_e32 v151, v152, v152
	v_add_f32_e32 v150, v150, v151
	v_mul_f32_e32 v151, v165, v165
	v_fmac_f32_e32 v151, v164, v164
	v_add_f32_e32 v166, v151, v150
	v_cvt_pk_bf16_f32 v150, v158, v159
	v_cvt_pk_bf16_f32 v151, v160, v161
	v_pk_add_f32 v[160:161], v[88:89], v[148:149]
	v_pk_add_f32 v[146:147], v[86:87], v[146:147]
	v_mul_f32_e32 v149, v161, v161
	v_mul_f32_e32 v148, v147, v147
	v_pk_add_f32 v[154:155], v[82:83], v[154:155]
	v_fmac_f32_e32 v148, v146, v146
	v_fmac_f32_e32 v149, v160, v160
	v_add_f32_e32 v148, v148, v149
	v_mul_f32_e32 v149, v155, v155
	v_pk_add_f32 v[156:157], v[84:85], v[156:157]
	v_fmac_f32_e32 v149, v154, v154
	v_add_f32_e32 v148, v148, v149
	v_mul_f32_e32 v149, v157, v157
	v_fmac_f32_e32 v149, v156, v156
	v_add_f32_e32 v148, v149, v148
	s_or_b32 s81, s51, 32
	v_cvt_pk_bf16_f32 v152, v152, v153
	v_cvt_pk_bf16_f32 v153, v164, v165
	v_add_f32_e32 v164, v166, v148
	v_add_u32_e32 v162, s81, v216
	v_mov_b32_e32 v165, v164
	v_mov_b32_e32 v247, v164
	s_nop 1
	v_permlane16_swap_b32_e32 v247, v165
	s_waitcnt lgkmcnt(1)
	v_ashrrev_i32_e32 v163, 31, v162
	v_lshlrev_b64 v[158:159], 11, v[162:163]
	v_lshl_add_u64 v[148:149], s[40:41], 0, v[158:159]
	v_lshl_add_u64 v[158:159], v[206:207], 1, v[148:149]
	global_store_dwordx4 v[158:159], v[150:153], off
	v_cvt_pk_bf16_f32 v148, v146, v147
	s_waitcnt lgkmcnt(0)
	v_add_f32_e32 v146, v164, v165
	v_mov_b32_e32 v147, v146
	v_mov_b32_e32 v247, v146
	s_nop 1
	v_permlane32_swap_b32_e32 v247, v147
	v_cvt_pk_bf16_f32 v149, v160, v161
	v_cvt_pk_bf16_f32 v150, v154, v155
	v_cvt_pk_bf16_f32 v151, v156, v157
	global_store_dwordx4 v[158:159], v[148:151], off offset:256
	s_and_saveexec_b64 s[62:63], s[58:59]
	s_cbranch_execz .LBB0_369
	v_lshlrev_b64 v[148:149], 6, v[162:163]
	v_lshl_add_u64 v[148:149], s[42:43], 0, v[148:149]
	v_lshl_add_u64 v[148:149], s[60:61], 2, v[148:149]
	s_lshl_b32 s70, s87, 2
	v_lshl_add_u64 v[148:149], v[148:149], 0, s[70:71]
	s_waitcnt lgkmcnt(0)
	v_add_f32_e32 v146, v146, v147
	global_store_dword v[148:149], v146, off
; __device__ __forceinline__ unsigned cvt_pk_bf16(float lo, float hi) { unsigned r; asm volatile("v_cvt_pk_bf16_f32 %0, %1, %2" : "=v"(r) : "v"(lo), "v"(hi)); return r; }
;     __device__ __forceinline__ void finish_half(const f32x4 (&acc)[2][2][4][2], const f32x4 (&r)[4][2][2], const Unit& u, int ai, int rl0, int col0, int wc, int fq) const {
;     ...
;         for (int m = 0; m < 4; ++m) { const size_t row = (size_t)(u.pm * BM + rl0 + ai * HALF + m * 16); const size_t off = row * 1024 + col0; float q = 0.f;
; #pragma unroll
;             for (int bj = 0; bj < 2; ++bj) {
;                 const f32x4 v0 = acc[ai][bj][m][0] + r[m][bj][0], v1 = acc[ai][bj][m][1] + r[m][bj][1];
;                 if (out32) { *(f32x4*)(out32 + off + bj * HALF) = v0; *(f32x4*)(out32 + off + bj * HALF + 4) = v1; }
;                 q += (v0[0] * v0[0] + v0[1] * v0[1]) + (v0[2] * v0[2] + v0[3] * v0[3]) + (v1[0] * v1[0] + v1[1] * v1[1]) + (v1[2] * v1[2] + v1[3] * v1[3]);
;                 u32x4 w; w.x = cvt_pk_bf16(v0[0], v0[1]); w.y = cvt_pk_bf16(v0[2], v0[3]); w.z = cvt_pk_bf16(v1[0], v1[1]); w.w = cvt_pk_bf16(v1[2], v1[3]);
;                 *(u32x4*)(hb + off + bj * HALF) = w; }
;             q += __shfl_xor(q, 16); q += __shfl_xor(q, 32);
;             if (fq == 0) ssq[row * 16 + u.pn * 4 + wc] = q; }
;     __device__ __forceinline__ void operator()(const f32x4 (&acc)[2][2][4][2], const Unit& u, int wr, int wc, int fr, int fq) const {
;     ...
;             for (int ai = 0; ai < 2; ++ai) { f32x4 r[4][2][2];
; #pragma unroll
;                 for (int m = 0; m < 4; ++m)
; #pragma unroll
;                     for (int bj = 0; bj < 2; ++bj) { const size_t off = (size_t)(u.pm * BM + rl0 + ai * HALF + m * 16) * 1024 + col0 + bj * HALF;
;                         r[m][bj][0] = *(const f32x4*)(res32 + off); r[m][bj][1] = *(const f32x4*)(res32 + off + 4); }
;                 finish_half(acc, r, u, ai, rl0, col0, wc, fq); }
.LBB0_369:
	s_or_b64 exec, exec, s[62:63]
	v_pk_add_f32 v[144:145], v[80:81], v[144:145]
	v_pk_add_f32 v[142:143], v[78:79], v[142:143]
	v_pk_add_f32 v[148:149], v[76:77], v[136:137]
	v_pk_add_f32 v[136:137], v[74:75], v[134:135]
	v_mul_f32_e32 v134, v143, v143
	v_mul_f32_e32 v135, v145, v145
	v_fmac_f32_e32 v134, v142, v142
	v_fmac_f32_e32 v135, v144, v144
	v_add_f32_e32 v134, v134, v135
	v_mul_f32_e32 v135, v137, v137
	v_fmac_f32_e32 v135, v136, v136
	v_add_f32_e32 v134, v134, v135
	v_mul_f32_e32 v135, v149, v149
	v_fmac_f32_e32 v135, v148, v148
	v_add_f32_e32 v150, v135, v134
	v_cvt_pk_bf16_f32 v134, v142, v143
	v_cvt_pk_bf16_f32 v135, v144, v145
	v_pk_add_f32 v[144:145], v[72:73], v[132:133]
	v_pk_add_f32 v[130:131], v[70:71], v[130:131]
	v_mul_f32_e32 v133, v145, v145
	v_mul_f32_e32 v132, v131, v131
	v_pk_add_f32 v[138:139], v[66:67], v[138:139]
	v_fmac_f32_e32 v132, v130, v130
	v_fmac_f32_e32 v133, v144, v144
	v_add_f32_e32 v132, v132, v133
	v_mul_f32_e32 v133, v139, v139
	v_pk_add_f32 v[140:141], v[68:69], v[140:141]
	v_fmac_f32_e32 v133, v138, v138
	v_add_f32_e32 v132, v132, v133
	v_mul_f32_e32 v133, v141, v141
	v_fmac_f32_e32 v133, v140, v140
	v_add_f32_e32 v132, v133, v132
	s_or_b32 s82, s51, 48
	v_cvt_pk_bf16_f32 v136, v136, v137
	v_cvt_pk_bf16_f32 v137, v148, v149
	v_add_f32_e32 v148, v150, v132
	v_add_u32_e32 v146, s82, v216
	v_mov_b32_e32 v149, v148
	v_mov_b32_e32 v247, v148
	s_nop 1
	v_permlane16_swap_b32_e32 v247, v149
	s_waitcnt lgkmcnt(1)
	v_ashrrev_i32_e32 v147, 31, v146
	v_lshlrev_b64 v[142:143], 11, v[146:147]
	v_lshl_add_u64 v[132:133], s[40:41], 0, v[142:143]
	v_lshl_add_u64 v[142:143], v[206:207], 1, v[132:133]
	global_store_dwordx4 v[142:143], v[134:137], off
	v_cvt_pk_bf16_f32 v132, v130, v131
	s_waitcnt lgkmcnt(0)
	v_add_f32_e32 v130, v148, v149
	v_mov_b32_e32 v131, v130
	v_mov_b32_e32 v247, v130
	s_nop 1
	v_permlane32_swap_b32_e32 v247, v131
	v_cvt_pk_bf16_f32 v133, v144, v145
	v_cvt_pk_bf16_f32 v134, v138, v139
	v_cvt_pk_bf16_f32 v135, v140, v141
	global_store_dwordx4 v[142:143], v[132:135], off offset:256
	s_and_saveexec_b64 s[62:63], s[58:59]
	s_cbranch_execz .LBB0_371
	v_lshlrev_b64 v[132:133], 6, v[146:147]
	v_lshl_add_u64 v[132:133], s[42:43], 0, v[132:133]
	v_lshl_add_u64 v[132:133], s[60:61], 2, v[132:133]
	s_lshl_b32 s70, s87, 2
	v_lshl_add_u64 v[132:133], v[132:133], 0, s[70:71]
	s_waitcnt lgkmcnt(0)
	v_add_f32_e32 v130, v130, v131
	global_store_dword v[132:133], v130, off
.LBB0_371:
	s_or_b64 exec, exec, s[62:63]
	s_waitcnt lgkmcnt(0)
	v_lshlrev_b64 v[130:131], 12, v[208:209]
	v_lshl_add_u64 v[130:131], v[178:179], 0, v[130:131]
	v_add_co_u32_e32 v134, vcc, 0x80000, v130
	s_mov_b64 s[62:63], 0x80000
	s_nop 0
	v_addc_co_u32_e32 v135, vcc, 0, v131, vcc
	v_lshl_add_u64 v[132:133], v[130:131], 0, s[62:63]
	global_load_dwordx4 v[218:221], v[134:135], off
	global_load_dwordx4 v[222:225], v[132:133], off offset:16
	global_load_dwordx4 v[178:181], v[132:133], off offset:528
	global_load_dwordx4 v[182:185], v[132:133], off offset:512
	v_add_co_u32_e32 v134, vcc, 0x90000, v130
	s_mov_b64 s[62:63], 0x90000
	s_nop 0
	v_addc_co_u32_e32 v135, vcc, 0, v131, vcc
	v_lshl_add_u64 v[132:133], v[130:131], 0, s[62:63]
	global_load_dwordx4 v[174:177], v[134:135], off
	global_load_dwordx4 v[170:173], v[132:133], off offset:16
	global_load_dwordx4 v[162:165], v[132:133], off offset:528
	global_load_dwordx4 v[166:169], v[132:133], off offset:512
	s_mov_b64 s[62:63], 0xa0000
	v_add_co_u32_e32 v134, vcc, 0xa0000, v130
	v_lshl_add_u64 v[132:133], v[130:131], 0, s[62:63]
	s_nop 0
	v_addc_co_u32_e32 v135, vcc, 0, v131, vcc
	s_mov_b64 s[62:63], 0xb0000
	v_lshl_add_u64 v[138:139], v[130:131], 0, s[62:63]
	v_add_co_u32_e32 v130, vcc, 0xb0000, v130
	global_load_dwordx4 v[158:161], v[134:135], off
	global_load_dwordx4 v[154:157], v[132:133], off offset:16
	global_load_dwordx4 v[142:145], v[132:133], off offset:528
	global_load_dwordx4 v[146:149], v[132:133], off offset:512
	v_addc_co_u32_e32 v131, vcc, 0, v131, vcc
	global_load_dwordx4 v[134:137], v[130:131], off
	global_load_dwordx4 v[150:153], v[138:139], off offset:16
	s_nop 0
	global_load_dwordx4 v[130:133], v[138:139], off offset:528
	s_nop 0
	global_load_dwordx4 v[138:141], v[138:139], off offset:512
	v_add_u32_e32 v212, 0x80, v216
	v_add_u32_e32 v210, s51, v212
	v_ashrrev_i32_e32 v211, 31, v210
	s_waitcnt vmcnt(15)
	v_pk_add_f32 v[220:221], v[64:65], v[220:221]
	v_pk_add_f32 v[218:219], v[62:63], v[218:219]
	v_mul_f32_e32 v226, v221, v221
	v_mul_f32_e32 v213, v219, v219
	s_waitcnt vmcnt(14)
	v_pk_add_f32 v[222:223], v[58:59], v[222:223]
	v_fmac_f32_e32 v213, v218, v218
	v_fmac_f32_e32 v226, v220, v220
	v_add_f32_e32 v213, v213, v226
	v_mul_f32_e32 v226, v223, v223
	v_fmac_f32_e32 v226, v222, v222
	v_cvt_pk_bf16_f32 v218, v218, v219
	v_cvt_pk_bf16_f32 v219, v220, v221
	v_cvt_pk_bf16_f32 v220, v222, v223
	v_lshlrev_b64 v[222:223], 11, v[210:211]
	v_lshl_add_u64 v[222:223], s[40:41], 0, v[222:223]
	v_lshl_add_u64 v[222:223], v[206:207], 1, v[222:223]
	s_waitcnt vmcnt(12)
	v_pk_add_f32 v[184:185], v[56:57], v[184:185]
	v_pk_add_f32 v[182:183], v[54:55], v[182:183]
	v_pk_add_f32 v[224:225], v[60:61], v[224:225]
	v_add_f32_e32 v213, v213, v226
	v_cvt_pk_bf16_f32 v221, v224, v225
	global_store_dwordx4 v[222:223], v[218:221], off
	v_mul_f32_e32 v226, v225, v225
	v_fmac_f32_e32 v226, v224, v224
	v_pk_add_f32 v[218:219], v[52:53], v[180:181]
	v_pk_add_f32 v[180:181], v[50:51], v[178:179]
	v_mul_f32_e32 v178, v183, v183
	v_mul_f32_e32 v179, v185, v185
	v_fmac_f32_e32 v178, v182, v182
	v_fmac_f32_e32 v179, v184, v184
	v_add_f32_e32 v178, v178, v179
	v_mul_f32_e32 v179, v181, v181
	v_fmac_f32_e32 v179, v180, v180
	v_add_f32_e32 v178, v178, v179
	v_mul_f32_e32 v179, v219, v219
	v_fmac_f32_e32 v179, v218, v218
	v_add_f32_e32 v213, v226, v213
	v_add_f32_e32 v178, v179, v178
	v_add_f32_e32 v213, v213, v178
	v_cvt_pk_bf16_f32 v178, v182, v183
	v_cvt_pk_bf16_f32 v179, v184, v185
	v_cvt_pk_bf16_f32 v180, v180, v181
	v_cvt_pk_bf16_f32 v181, v218, v219
	global_store_dwordx4 v[222:223], v[178:181], off offset:256
	s_nop 1
	v_mov_b32_e32 v178, v213
	v_mov_b32_e32 v247, v213
	s_nop 1
	v_permlane16_swap_b32_e32 v247, v178
	s_waitcnt lgkmcnt(0)
	v_add_f32_e32 v178, v213, v178
	v_mov_b32_e32 v179, v178
	v_mov_b32_e32 v247, v178
	s_nop 1
	v_permlane32_swap_b32_e32 v247, v179
	s_and_saveexec_b64 s[62:63], s[58:59]
	s_cbranch_execz .LBB0_373
	v_lshlrev_b64 v[180:181], 6, v[210:211]
	v_lshl_add_u64 v[180:181], s[42:43], 0, v[180:181]
	v_lshl_add_u64 v[180:181], s[60:61], 2, v[180:181]
	s_lshl_b32 s70, s87, 2
	v_lshl_add_u64 v[180:181], v[180:181], 0, s[70:71]
	s_waitcnt lgkmcnt(0)
	v_add_f32_e32 v178, v178, v179
	global_store_dword v[180:181], v178, off
; __device__ __forceinline__ unsigned cvt_pk_bf16(float lo, float hi) { unsigned r; asm volatile("v_cvt_pk_bf16_f32 %0, %1, %2" : "=v"(r) : "v"(lo), "v"(hi)); return r; }
;     __device__ __forceinline__ void finish_half(const f32x4 (&acc)[2][2][4][2], const f32x4 (&r)[4][2][2], const Unit& u, int ai, int rl0, int col0, int wc, int fq) const {
;     ...
;         for (int m = 0; m < 4; ++m) { const size_t row = (size_t)(u.pm * BM + rl0 + ai * HALF + m * 16); const size_t off = row * 1024 + col0; float q = 0.f;
; #pragma unroll
;             for (int bj = 0; bj < 2; ++bj) {
;                 const f32x4 v0 = acc[ai][bj][m][0] + r[m][bj][0], v1 = acc[ai][bj][m][1] + r[m][bj][1];
;                 if (out32) { *(f32x4*)(out32 + off + bj * HALF) = v0; *(f32x4*)(out32 + off + bj * HALF + 4) = v1; }
;                 q += (v0[0] * v0[0] + v0[1] * v0[1]) + (v0[2] * v0[2] + v0[3] * v0[3]) + (v1[0] * v1[0] + v1[1] * v1[1]) + (v1[2] * v1[2] + v1[3] * v1[3]);
;                 u32x4 w; w.x = cvt_pk_bf16(v0[0], v0[1]); w.y = cvt_pk_bf16(v0[2], v0[3]); w.z = cvt_pk_bf16(v1[0], v1[1]); w.w = cvt_pk_bf16(v1[2], v1[3]);
;                 *(u32x4*)(hb + off + bj * HALF) = w; }
;             q += __shfl_xor(q, 16); q += __shfl_xor(q, 32);
;             if (fq == 0) ssq[row * 16 + u.pn * 4 + wc] = q; }
.LBB0_373:
	s_or_b64 exec, exec, s[62:63]
	s_waitcnt vmcnt(13)
	v_pk_add_f32 v[176:177], v[48:49], v[176:177]
	v_pk_add_f32 v[174:175], v[46:47], v[174:175]
	s_waitcnt vmcnt(12)
	v_pk_add_f32 v[180:181], v[44:45], v[172:173]
	v_pk_add_f32 v[172:173], v[42:43], v[170:171]
	v_mul_f32_e32 v170, v175, v175
	v_mul_f32_e32 v171, v177, v177
	v_fmac_f32_e32 v170, v174, v174
	v_fmac_f32_e32 v171, v176, v176
	v_add_f32_e32 v170, v170, v171
	v_mul_f32_e32 v171, v173, v173
	v_fmac_f32_e32 v171, v172, v172
	v_add_f32_e32 v170, v170, v171
	v_mul_f32_e32 v171, v181, v181
	v_fmac_f32_e32 v171, v180, v180
	s_waitcnt vmcnt(10)
	v_pk_add_f32 v[168:169], v[40:41], v[168:169]
	v_pk_add_f32 v[166:167], v[38:39], v[166:167]
	v_add_f32_e32 v182, v171, v170
	v_cvt_pk_bf16_f32 v170, v174, v175
	v_cvt_pk_bf16_f32 v171, v176, v177
	v_cvt_pk_bf16_f32 v172, v172, v173
	v_cvt_pk_bf16_f32 v173, v180, v181
	v_pk_add_f32 v[180:181], v[34:35], v[162:163]
	v_mul_f32_e32 v162, v167, v167
	v_mul_f32_e32 v163, v169, v169
	v_fmac_f32_e32 v162, v166, v166
	v_fmac_f32_e32 v163, v168, v168
	v_add_f32_e32 v162, v162, v163
	v_mul_f32_e32 v163, v181, v181
	v_pk_add_f32 v[176:177], v[36:37], v[164:165]
	v_fmac_f32_e32 v163, v180, v180
	v_add_f32_e32 v162, v162, v163
	v_mul_f32_e32 v163, v177, v177
	v_fmac_f32_e32 v163, v176, v176
	v_add_f32_e32 v162, v163, v162
	v_add_f32_e32 v165, v182, v162
	v_mov_b32_e32 v182, v165
	v_mov_b32_e32 v247, v165
	s_nop 1
	v_permlane16_swap_b32_e32 v247, v182
	v_add_u32_e32 v178, s53, v212
	s_waitcnt lgkmcnt(1)
	v_ashrrev_i32_e32 v179, 31, v178
	v_lshlrev_b64 v[174:175], 11, v[178:179]
	v_lshl_add_u64 v[162:163], s[40:41], 0, v[174:175]
	v_lshl_add_u64 v[174:175], v[206:207], 1, v[162:163]
	s_waitcnt lgkmcnt(0)
	v_add_f32_e32 v162, v165, v182
	v_mov_b32_e32 v163, v162
	v_mov_b32_e32 v247, v162
	s_nop 1
	v_permlane32_swap_b32_e32 v247, v163
	global_store_dwordx4 v[174:175], v[170:173], off
	v_cvt_pk_bf16_f32 v164, v166, v167
	v_cvt_pk_bf16_f32 v165, v168, v169
	v_cvt_pk_bf16_f32 v166, v180, v181
	v_cvt_pk_bf16_f32 v167, v176, v177
	global_store_dwordx4 v[174:175], v[164:167], off offset:256
	s_and_saveexec_b64 s[62:63], s[58:59]
	s_cbranch_execz .LBB0_375
	v_lshlrev_b64 v[164:165], 6, v[178:179]
	v_lshl_add_u64 v[164:165], s[42:43], 0, v[164:165]
	v_lshl_add_u64 v[164:165], s[60:61], 2, v[164:165]
	s_lshl_b32 s70, s87, 2
	v_lshl_add_u64 v[164:165], v[164:165], 0, s[70:71]
	s_waitcnt lgkmcnt(0)
	v_add_f32_e32 v162, v162, v163
	global_store_dword v[164:165], v162, off
; __device__ __forceinline__ unsigned cvt_pk_bf16(float lo, float hi) { unsigned r; asm volatile("v_cvt_pk_bf16_f32 %0, %1, %2" : "=v"(r) : "v"(lo), "v"(hi)); return r; }
;     __device__ __forceinline__ void finish_half(const f32x4 (&acc)[2][2][4][2], const f32x4 (&r)[4][2][2], const Unit& u, int ai, int rl0, int col0, int wc, int fq) const {
;     ...
;         for (int m = 0; m < 4; ++m) { const size_t row = (size_t)(u.pm * BM + rl0 + ai * HALF + m * 16); const size_t off = row * 1024 + col0; float q = 0.f;
; #pragma unroll
;             for (int bj = 0; bj < 2; ++bj) {
;                 const f32x4 v0 = acc[ai][bj][m][0] + r[m][bj][0], v1 = acc[ai][bj][m][1] + r[m][bj][1];
;                 if (out32) { *(f32x4*)(out32 + off + bj * HALF) = v0; *(f32x4*)(out32 + off + bj * HALF + 4) = v1; }
;                 q += (v0[0] * v0[0] + v0[1] * v0[1]) + (v0[2] * v0[2] + v0[3] * v0[3]) + (v1[0] * v1[0] + v1[1] * v1[1]) + (v1[2] * v1[2] + v1[3] * v1[3]);
;                 u32x4 w; w.x = cvt_pk_bf16(v0[0], v0[1]); w.y = cvt_pk_bf16(v0[2], v0[3]); w.z = cvt_pk_bf16(v1[0], v1[1]); w.w = cvt_pk_bf16(v1[2], v1[3]);
;                 *(u32x4*)(hb + off + bj * HALF) = w; }
;             q += __shfl_xor(q, 16); q += __shfl_xor(q, 32);
;             if (fq == 0) ssq[row * 16 + u.pn * 4 + wc] = q; }
.LBB0_375:
	s_or_b64 exec, exec, s[62:63]
	s_waitcnt vmcnt(11)
	v_pk_add_f32 v[160:161], v[32:33], v[160:161]
	v_pk_add_f32 v[158:159], v[30:31], v[158:159]
	s_waitcnt vmcnt(10)
	v_pk_add_f32 v[164:165], v[28:29], v[156:157]
	v_pk_add_f32 v[156:157], v[26:27], v[154:155]
	v_mul_f32_e32 v154, v159, v159
	v_mul_f32_e32 v155, v161, v161
	v_fmac_f32_e32 v154, v158, v158
	v_fmac_f32_e32 v155, v160, v160
	v_add_f32_e32 v154, v154, v155
	v_mul_f32_e32 v155, v157, v157
	v_fmac_f32_e32 v155, v156, v156
	v_add_f32_e32 v154, v154, v155
	v_mul_f32_e32 v155, v165, v165
	v_fmac_f32_e32 v155, v164, v164
	s_waitcnt vmcnt(8)
	v_pk_add_f32 v[148:149], v[24:25], v[148:149]
	v_pk_add_f32 v[146:147], v[22:23], v[146:147]
	v_add_f32_e32 v166, v155, v154
	v_cvt_pk_bf16_f32 v154, v158, v159
	v_cvt_pk_bf16_f32 v155, v160, v161
	v_cvt_pk_bf16_f32 v156, v156, v157
	v_cvt_pk_bf16_f32 v157, v164, v165
	v_pk_add_f32 v[164:165], v[18:19], v[142:143]
	v_mul_f32_e32 v142, v147, v147
	v_mul_f32_e32 v143, v149, v149
	v_fmac_f32_e32 v142, v146, v146
	v_fmac_f32_e32 v143, v148, v148
	v_add_f32_e32 v142, v142, v143
	v_mul_f32_e32 v143, v165, v165
	v_pk_add_f32 v[160:161], v[20:21], v[144:145]
	v_fmac_f32_e32 v143, v164, v164
	v_add_f32_e32 v142, v142, v143
	v_mul_f32_e32 v143, v161, v161
	v_fmac_f32_e32 v143, v160, v160
	v_add_f32_e32 v142, v143, v142
	v_add_f32_e32 v145, v166, v142
	v_mov_b32_e32 v166, v145
	v_mov_b32_e32 v247, v145
	s_nop 1
	v_permlane16_swap_b32_e32 v247, v166
	v_add_u32_e32 v162, s81, v212
	s_waitcnt lgkmcnt(1)
	v_ashrrev_i32_e32 v163, 31, v162
	v_lshlrev_b64 v[158:159], 11, v[162:163]
	v_lshl_add_u64 v[142:143], s[40:41], 0, v[158:159]
	v_lshl_add_u64 v[158:159], v[206:207], 1, v[142:143]
	s_waitcnt lgkmcnt(0)
	v_add_f32_e32 v142, v145, v166
	v_mov_b32_e32 v143, v142
	v_mov_b32_e32 v247, v142
	s_nop 1
	v_permlane32_swap_b32_e32 v247, v143
	global_store_dwordx4 v[158:159], v[154:157], off
	v_cvt_pk_bf16_f32 v144, v146, v147
	v_cvt_pk_bf16_f32 v145, v148, v149
	v_cvt_pk_bf16_f32 v146, v164, v165
	v_cvt_pk_bf16_f32 v147, v160, v161
	global_store_dwordx4 v[158:159], v[144:147], off offset:256
	s_and_saveexec_b64 s[62:63], s[58:59]
	s_cbranch_execz .LBB0_377
	v_lshlrev_b64 v[144:145], 6, v[162:163]
	v_lshl_add_u64 v[144:145], s[42:43], 0, v[144:145]
	v_lshl_add_u64 v[144:145], s[60:61], 2, v[144:145]
	s_lshl_b32 s70, s87, 2
	v_lshl_add_u64 v[144:145], v[144:145], 0, s[70:71]
	s_waitcnt lgkmcnt(0)
	v_add_f32_e32 v142, v142, v143
	global_store_dword v[144:145], v142, off
.LBB0_377:
	s_or_b64 exec, exec, s[62:63]
	v_add_u32_e32 v142, s82, v212
	s_waitcnt lgkmcnt(0)
	v_ashrrev_i32_e32 v143, 31, v142
	s_waitcnt vmcnt(8)
	v_pk_add_f32 v[148:149], v[12:13], v[152:153]
	v_lshlrev_b64 v[152:153], 11, v[142:143]
	v_lshl_add_u64 v[152:153], s[40:41], 0, v[152:153]
	v_pk_add_f32 v[144:145], v[16:17], v[136:137]
	v_pk_add_f32 v[146:147], v[14:15], v[134:135]
	v_pk_add_f32 v[150:151], v[10:11], v[150:151]
	v_cvt_pk_bf16_f32 v134, v146, v147
	v_cvt_pk_bf16_f32 v135, v144, v145
	v_lshl_add_u64 v[152:153], v[206:207], 1, v[152:153]
	v_cvt_pk_bf16_f32 v136, v150, v151
	v_cvt_pk_bf16_f32 v137, v148, v149
	global_store_dwordx4 v[152:153], v[134:137], off
	s_waitcnt vmcnt(7)
	s_nop 0
	v_pk_add_f32 v[136:137], v[6:7], v[138:139]
	v_pk_add_f32 v[134:135], v[8:9], v[140:141]
	v_mov_b32_e32 v140, v147
	v_mov_b32_e32 v141, v137
	v_pk_add_f32 v[138:139], v[4:5], v[132:133]
	v_pk_add_f32 v[132:133], v[2:3], v[130:131]
	v_mov_b32_e32 v130, v146
	v_mov_b32_e32 v131, v136
	v_pk_mul_f32 v[140:141], v[140:141], v[140:141]
	s_nop 0
	v_pk_fma_f32 v[130:131], v[130:131], v[130:131], v[140:141]
	v_mov_b32_e32 v140, v144
	v_mov_b32_e32 v144, v145
	v_mov_b32_e32 v145, v135
	v_mov_b32_e32 v141, v134
	v_pk_mul_f32 v[144:145], v[144:145], v[144:145]
	s_nop 0
	v_pk_fma_f32 v[140:141], v[140:141], v[140:141], v[144:145]
	v_mov_b32_e32 v144, v151
	v_mov_b32_e32 v145, v133
	v_pk_add_f32 v[130:131], v[130:131], v[140:141]
	v_mov_b32_e32 v140, v150
	v_mov_b32_e32 v141, v132
	v_pk_mul_f32 v[144:145], v[144:145], v[144:145]
	s_nop 0
	v_pk_fma_f32 v[140:141], v[140:141], v[140:141], v[144:145]
	v_mov_b32_e32 v144, v149
	v_mov_b32_e32 v145, v139
	v_pk_add_f32 v[130:131], v[130:131], v[140:141]
	v_mov_b32_e32 v140, v148
	v_mov_b32_e32 v141, v138
	v_pk_mul_f32 v[144:145], v[144:145], v[144:145]
	s_nop 0
	v_pk_fma_f32 v[140:141], v[140:141], v[140:141], v[144:145]
	s_nop 0
	v_pk_add_f32 v[130:131], v[140:141], v[130:131]
	s_nop 0
	v_add_f32_e32 v140, v130, v131
	v_cvt_pk_bf16_f32 v130, v136, v137
	v_cvt_pk_bf16_f32 v131, v134, v135
	v_cvt_pk_bf16_f32 v132, v132, v133
	v_cvt_pk_bf16_f32 v133, v138, v139
	global_store_dwordx4 v[152:153], v[130:133], off offset:256
	s_nop 1
	v_mov_b32_e32 v130, v140
	v_mov_b32_e32 v247, v140
	s_nop 1
	v_permlane16_swap_b32_e32 v247, v130
	s_waitcnt lgkmcnt(0)
	v_add_f32_e32 v130, v140, v130
	v_mov_b32_e32 v131, v130
	v_mov_b32_e32 v247, v130
	s_nop 1
	v_permlane32_swap_b32_e32 v247, v131
